# SWA loop: drop the vmcnt(3..0) ladder after the tile barrier (every wave already drained at the loop top; it only waited for the just-issued next-tile prefetch)
# baseline (speedup 1.0000x reference)
; __device__ __forceinline__ void swa_attn_phase(const bf16* QKV, const float* sinks, bf16* AO, LAS unsigned char* lds, int vcu, int G) {
;     ...
;         for (int T = Tfirst; T <= Tlast; ++T) {
;             stage_write(lds + (T & 3) * ABUF, ra, rb, tid);
;             if (T < Tlast) { ra = *(const v4u*)(gA + (size_t)(T + 1) * 64 * N_SWA_IN); rb = *(const v4u*)(gB + (size_t)(T + 1) * 64 * N_SWA_IN); }
;             __syncthreads();
;             if (T >= Q0) {
;                 bf16x8 qr[4];
; #pragma unroll
;                 for (int d0 = 0; d0 < 4; ++d0) qr[d0] = scale_q(qn[d0]);
;                 if (T < Tlast) {
; #pragma unroll
;                     for (int d0 = 0; d0 < 4; ++d0) qn[d0] = *(const v4u*)(Qb + (size_t)(T + 1) * 64 * N_SWA_IN + d0 * 16);
;                 }
.LBB0_270:
	s_cmp_lt_i32 s28, s24
	s_waitcnt lgkmcnt(0)
	s_barrier
	s_cbranch_scc1 .LBB0_263
	s_nop 0
	v_mov_b64_e32 v[78:79], v[4:5]
	s_nop 0
	v_mov_b64_e32 v[82:83], v[30:31]
	s_nop 0
	v_mov_b64_e32 v[86:87], v[26:27]
	s_nop 0
	v_mov_b64_e32 v[90:91], v[22:23]
	s_andn2_b64 vcc, exec, s[16:17]
	v_mov_b64_e32 v[76:77], v[2:3]
	v_mov_b64_e32 v[80:81], v[28:29]
	v_mov_b64_e32 v[84:85], v[24:25]
	v_mov_b64_e32 v[88:89], v[20:21]
	s_cbranch_vccnz .LBB0_273
	s_add_i32 s16, s19, 3
	v_mad_u64_u32 v[6:7], s[16:17], s16, v196, v[168:169]
	global_load_dwordx4 v[76:79], v[6:7], off
	global_load_dwordx4 v[80:83], v[6:7], off offset:32
	global_load_dwordx4 v[84:87], v[6:7], off offset:64
	global_load_dwordx4 v[88:91], v[6:7], off offset:96
